# phase-2 item table re-balanced with probe-calibrated model 0.49*nj+0.54*NS+11.3
# speedup vs baseline: 1.0021x; 1.0021x over previous
_ZL7idx_tab:
	.short	212
	.short	147
	.short	204
	.short	71
	.short	65535
	.short	340
	.short	339
	.short	268
	.short	263
	.short	65535
	.short	660
	.short	723
	.short	652
	.short	519
	.short	65535
	.short	916
	.short	979
	.short	972
	.short	775
	.short	65535
	.short	1236
	.short	1043
	.short	1100
	.short	1223
	.short	65535
	.short	1300
	.short	1427
	.short	1292
	.short	1479
	.short	65535
	.short	1748
	.short	1683
	.short	1612
	.short	1671
	.short	65535
	.short	2004
	.short	1811
	.short	1804
	.short	1863
	.short	65535
	.short	20
	.short	18
	.short	140
	.short	199
	.short	65535
	.short	468
	.short	274
	.short	460
	.short	327
	.short	65535
	.short	724
	.short	594
	.short	588
	.short	583
	.short	65535
	.short	980
	.short	786
	.short	780
	.short	903
	.short	65535
	.short	1044
	.short	1170
	.short	1228
	.short	1159
	.short	65535
	.short	1364
	.short	1298
	.short	1484
	.short	1351
	.short	65535
	.short	1556
	.short	1554
	.short	1548
	.short	1607
	.short	65535
	.short	1876
	.short	1938
	.short	1932
	.short	1927
	.short	65535
	.short	32
	.short	85
	.short	21
	.short	65535
	.short	65535
	.short	224
	.short	469
	.short	405
	.short	65535
	.short	65535
	.short	352
	.short	725
	.short	661
	.short	65535
	.short	65535
	.short	416
	.short	853
	.short	789
	.short	65535
	.short	65535
	.short	608
	.short	1173
	.short	1045
	.short	65535
	.short	65535
	.short	672
	.short	1365
	.short	1493
	.short	65535
	.short	65535
	.short	800
	.short	1621
	.short	1685
	.short	65535
	.short	65535
	.short	928
	.short	1813
	.short	2005
	.short	65535
	.short	65535
	.short	96
	.short	151
	.short	146
	.short	65535
	.short	65535
	.short	160
	.short	471
	.short	338
	.short	65535
	.short	65535
	.short	288
	.short	599
	.short	530
	.short	65535
	.short	65535
	.short	480
	.short	855
	.short	978
	.short	65535
	.short	65535
	.short	544
	.short	1175
	.short	1042
	.short	65535
	.short	65535
	.short	736
	.short	1303
	.short	1490
	.short	65535
	.short	65535
	.short	864
	.short	1559
	.short	1746
	.short	65535
	.short	65535
	.short	992
	.short	1943
	.short	1874
	.short	65535
	.short	65535
	.short	31
	.short	219
	.short	207
	.short	65
	.short	65535
	.short	351
	.short	411
	.short	463
	.short	321
	.short	65535
	.short	671
	.short	603
	.short	591
	.short	704
	.short	65535
	.short	863
	.short	987
	.short	783
	.short	770
	.short	65535
	.short	1119
	.short	1051
	.short	1039
	.short	1025
	.short	65535
	.short	1311
	.short	1371
	.short	1359
	.short	1282
	.short	65535
	.short	1567
	.short	1627
	.short	1743
	.short	1729
	.short	65535
	.short	1887
	.short	2011
	.short	1871
	.short	1985
	.short	65535
	.short	223
	.short	91
	.short	79
	.short	193
	.short	65535
	.short	479
	.short	347
	.short	335
	.short	387
	.short	65535
	.short	543
	.short	667
	.short	655
	.short	513
	.short	65535
	.short	927
	.short	795
	.short	847
	.short	834
	.short	65535
	.short	1183
	.short	1179
	.short	1167
	.short	1153
	.short	65535
	.short	1439
	.short	1499
	.short	1423
	.short	1344
	.short	65535
	.short	1631
	.short	1563
	.short	1679
	.short	1667
	.short	65535
	.short	1951
	.short	1819
	.short	1935
	.short	1857
	.short	65535
	.short	95
	.short	26
	.short	143
	.short	194
	.short	65535
	.short	287
	.short	282
	.short	399
	.short	448
	.short	65535
	.short	735
	.short	666
	.short	527
	.short	641
	.short	65535
	.short	799
	.short	986
	.short	911
	.short	897
	.short	65535
	.short	1247
	.short	1242
	.short	1103
	.short	1089
	.short	65535
	.short	1503
	.short	1498
	.short	1487
	.short	1281
	.short	65535
	.short	1695
	.short	1562
	.short	1615
	.short	1602
	.short	65535
	.short	2015
	.short	1818
	.short	1999
	.short	1921
	.short	65535
	.short	159
	.short	154
	.short	15
	.short	64
	.short	65535
	.short	415
	.short	474
	.short	271
	.short	386
	.short	65535
	.short	607
	.short	538
	.short	719
	.short	512
	.short	65535
	.short	991
	.short	794
	.short	975
	.short	768
	.short	65535
	.short	1055
	.short	1050
	.short	1231
	.short	1217
	.short	65535
	.short	1375
	.short	1434
	.short	1295
	.short	1475
	.short	65535
	.short	1759
	.short	1690
	.short	1551
	.short	1539
	.short	65535
	.short	1823
	.short	1882
	.short	1807
	.short	1793
	.short	65535
	.short	152
	.short	208
	.short	9
	.short	132
	.short	65535
	.short	344
	.short	336
	.short	329
	.short	324
	.short	65535
	.short	600
	.short	592
	.short	521
	.short	708
	.short	65535
	.short	792
	.short	912
	.short	841
	.short	836
	.short	65535
	.short	1112
	.short	1168
	.short	1097
	.short	1028
	.short	65535
	.short	1368
	.short	1488
	.short	1481
	.short	1284
	.short	65535
	.short	1624
	.short	1552
	.short	1609
	.short	1604
	.short	65535
	.short	1816
	.short	1808
	.short	1929
	.short	1988
	.short	65535
	.short	88
	.short	209
	.short	200
	.short	4
	.short	65535
	.short	280
	.short	465
	.short	392
	.short	260
	.short	65535
	.short	664
	.short	657
	.short	520
	.short	516
	.short	65535
	.short	920
	.short	913
	.short	776
	.short	964
	.short	65535
	.short	1048
	.short	1105
	.short	1160
	.short	1220
	.short	65535
	.short	1432
	.short	1297
	.short	1288
	.short	1412
	.short	65535
	.short	1688
	.short	1681
	.short	1608
	.short	1732
	.short	65535
	.short	1880
	.short	1809
	.short	1864
	.short	1860
	.short	65535
	.short	23
	.short	211
	.short	76
	.short	70
	.short	65535
	.short	343
	.short	403
	.short	396
	.short	326
	.short	65535
	.short	663
	.short	595
	.short	524
	.short	518
	.short	65535
	.short	919
	.short	915
	.short	908
	.short	966
	.short	65535
	.short	1111
	.short	1171
	.short	1164
	.short	1222
	.short	65535
	.short	1367
	.short	1299
	.short	1420
	.short	1478
	.short	65535
	.short	1751
	.short	1555
	.short	1740
	.short	1734
	.short	65535
	.short	2007
	.short	1875
	.short	1996
	.short	1862
	.short	65535
	.short	150
	.short	214
	.short	75
	.short	198
	.short	65535
	.short	342
	.short	278
	.short	267
	.short	454
	.short	65535
	.short	534
	.short	726
	.short	587
	.short	582
	.short	65535
	.short	790
	.short	918
	.short	971
	.short	902
	.short	65535
	.short	1110
	.short	1046
	.short	1163
	.short	1094
	.short	65535
	.short	1494
	.short	1366
	.short	1483
	.short	1286
	.short	65535
	.short	1622
	.short	1750
	.short	1611
	.short	1542
	.short	65535
	.short	1814
	.short	1878
	.short	1867
	.short	1990
	.short	65535
	.short	93
	.short	22
	.short	149
	.short	195
	.short	128
	.short	477
	.short	406
	.short	277
	.short	258
	.short	257
	.short	541
	.short	662
	.short	597
	.short	707
	.short	576
	.short	925
	.short	982
	.short	917
	.short	771
	.short	960
	.short	1245
	.short	1174
	.short	1237
	.short	1155
	.short	1091
	.short	1309
	.short	1430
	.short	1429
	.short	1283
	.short	1280
	.short	1757
	.short	1558
	.short	1557
	.short	1731
	.short	1600
	.short	1885
	.short	1942
	.short	1877
	.short	1923
	.short	1792
	.short	29
	.short	87
	.short	213
	.short	2
	.short	192
	.short	413
	.short	279
	.short	341
	.short	323
	.short	385
	.short	733
	.short	535
	.short	533
	.short	578
	.short	579
	.short	797
	.short	983
	.short	981
	.short	835
	.short	833
	.short	1053
	.short	1239
	.short	1109
	.short	1026
	.short	1024
	.short	1437
	.short	1431
	.short	1301
	.short	1409
	.short	1408
	.short	1693
	.short	1623
	.short	1749
	.short	1538
	.short	1728
	.short	1821
	.short	1815
	.short	1941
	.short	1987
	.short	1920
	.short	157
	.short	220
	.short	142
	.short	66
	.short	1
	.short	285
	.short	476
	.short	398
	.short	256
	.short	449
	.short	669
	.short	732
	.short	526
	.short	642
	.short	514
	.short	861
	.short	860
	.short	846
	.short	769
	.short	961
	.short	1181
	.short	1116
	.short	1038
	.short	1027
	.short	1152
	.short	1373
	.short	1436
	.short	1358
	.short	1347
	.short	1345
	.short	1629
	.short	1756
	.short	1678
	.short	1536
	.short	1665
	.short	1949
	.short	2012
	.short	1934
	.short	1858
	.short	1856
	.short	221
	.short	156
	.short	78
	.short	67
	.short	129
	.short	349
	.short	348
	.short	334
	.short	384
	.short	320
	.short	605
	.short	604
	.short	590
	.short	515
	.short	640
	.short	989
	.short	924
	.short	974
	.short	896
	.short	832
	.short	1117
	.short	1180
	.short	1230
	.short	1088
	.short	1216
	.short	1501
	.short	1372
	.short	1294
	.short	1474
	.short	1473
	.short	1565
	.short	1692
	.short	1550
	.short	1664
	.short	1601
	.short	2013
	.short	1820
	.short	1998
	.short	1859
	.short	1984
	.short	28
	.short	206
	.short	12
	.short	6
	.short	65535
	.short	284
	.short	462
	.short	332
	.short	390
	.short	65535
	.short	540
	.short	718
	.short	716
	.short	646
	.short	65535
	.short	988
	.short	782
	.short	844
	.short	774
	.short	65535
	.short	1244
	.short	1102
	.short	1036
	.short	1030
	.short	65535
	.short	1500
	.short	1422
	.short	1356
	.short	1350
	.short	65535
	.short	1564
	.short	1742
	.short	1676
	.short	1606
	.short	65535
	.short	1948
	.short	1870
	.short	1868
	.short	1798
	.short	65535
	.short	92
	.short	14
	.short	139
	.short	134
	.short	65535
	.short	412
	.short	270
	.short	395
	.short	262
	.short	65535
	.short	668
	.short	654
	.short	715
	.short	710
	.short	65535
	.short	796
	.short	910
	.short	907
	.short	838
	.short	65535
	.short	1052
	.short	1166
	.short	1227
	.short	1158
	.short	65535
	.short	1308
	.short	1486
	.short	1291
	.short	1414
	.short	65535
	.short	1628
	.short	1614
	.short	1739
	.short	1670
	.short	65535
	.short	1884
	.short	1806
	.short	1803
	.short	1926
	.short	65535
	.short	86
	.short	84
	.short	77
	.short	197
	.short	65535
	.short	470
	.short	404
	.short	269
	.short	453
	.short	65535
	.short	598
	.short	596
	.short	589
	.short	581
	.short	65535
	.short	854
	.short	852
	.short	781
	.short	773
	.short	65535
	.short	1238
	.short	1172
	.short	1037
	.short	1093
	.short	65535
	.short	1302
	.short	1428
	.short	1357
	.short	1349
	.short	65535
	.short	1686
	.short	1684
	.short	1613
	.short	1605
	.short	65535
	.short	2006
	.short	1812
	.short	1869
	.short	1797
	.short	65535
	.short	148
	.short	19
	.short	205
	.short	133
	.short	65535
	.short	276
	.short	275
	.short	461
	.short	325
	.short	65535
	.short	532
	.short	531
	.short	717
	.short	709
	.short	65535
	.short	788
	.short	787
	.short	909
	.short	837
	.short	65535
	.short	1108
	.short	1235
	.short	1165
	.short	1157
	.short	65535
	.short	1492
	.short	1491
	.short	1485
	.short	1477
	.short	65535
	.short	1620
	.short	1747
	.short	1741
	.short	1541
	.short	65535
	.short	1940
	.short	2003
	.short	1933
	.short	1925
	.short	65535
	.short	17
	.short	16
	.short	203
	.short	74
	.short	65535
	.short	337
	.short	272
	.short	331
	.short	394
	.short	65535
	.short	529
	.short	720
	.short	651
	.short	586
	.short	65535
	.short	849
	.short	976
	.short	843
	.short	906
	.short	65535
	.short	1169
	.short	1232
	.short	1099
	.short	1098
	.short	65535
	.short	1489
	.short	1296
	.short	1419
	.short	1418
	.short	65535
	.short	1553
	.short	1680
	.short	1675
	.short	1546
	.short	65535
	.short	1873
	.short	2000
	.short	1995
	.short	1802
	.short	65535
	.short	82
	.short	145
	.short	10
	.short	73
	.short	65535
	.short	402
	.short	273
	.short	266
	.short	393
	.short	65535
	.short	722
	.short	593
	.short	522
	.short	713
	.short	65535
	.short	914
	.short	785
	.short	970
	.short	777
	.short	65535
	.short	1106
	.short	1233
	.short	1226
	.short	1225
	.short	65535
	.short	1362
	.short	1361
	.short	1354
	.short	1353
	.short	65535
	.short	1618
	.short	1617
	.short	1610
	.short	1737
	.short	65535
	.short	2002
	.short	2001
	.short	1930
	.short	1993
	.short	65535
	.short	89
	.short	144
	.short	72
	.short	68
	.short	65535
	.short	473
	.short	464
	.short	328
	.short	388
	.short	65535
	.short	729
	.short	528
	.short	712
	.short	644
	.short	65535
	.short	985
	.short	784
	.short	968
	.short	900
	.short	65535
	.short	1177
	.short	1104
	.short	1096
	.short	1092
	.short	65535
	.short	1433
	.short	1424
	.short	1352
	.short	1348
	.short	65535
	.short	1689
	.short	1744
	.short	1544
	.short	1540
	.short	65535
	.short	1817
	.short	1936
	.short	1928
	.short	1796
	.short	65535
	.short	24
	.short	80
	.short	201
	.short	196
	.short	65535
	.short	472
	.short	400
	.short	457
	.short	452
	.short	65535
	.short	536
	.short	656
	.short	585
	.short	580
	.short	65535
	.short	984
	.short	848
	.short	969
	.short	772
	.short	65535
	.short	1176
	.short	1040
	.short	1033
	.short	1156
	.short	65535
	.short	1304
	.short	1360
	.short	1289
	.short	1476
	.short	65535
	.short	1560
	.short	1616
	.short	1673
	.short	1668
	.short	65535
	.short	1944
	.short	1872
	.short	1865
	.short	1924
	.short	65535
	.short	218
	.short	138
	.short	137
	.short	136
	.short	65535
	.short	346
	.short	330
	.short	265
	.short	456
	.short	65535
	.short	602
	.short	714
	.short	649
	.short	584
	.short	65535
	.short	858
	.short	842
	.short	905
	.short	840
	.short	65535
	.short	1178
	.short	1034
	.short	1161
	.short	1032
	.short	65535
	.short	1370
	.short	1482
	.short	1417
	.short	1480
	.short	65535
	.short	1754
	.short	1738
	.short	1545
	.short	1736
	.short	65535
	.short	1946
	.short	1994
	.short	1801
	.short	1800
	.short	65535
	.short	155
	.short	83
	.short	135
	.short	7
	.short	65535
	.short	475
	.short	467
	.short	455
	.short	391
	.short	65535
	.short	539
	.short	659
	.short	711
	.short	647
	.short	65535
	.short	859
	.short	851
	.short	839
	.short	967
	.short	65535
	.short	1115
	.short	1107
	.short	1095
	.short	1031
	.short	65535
	.short	1435
	.short	1363
	.short	1287
	.short	1415
	.short	65535
	.short	1755
	.short	1619
	.short	1543
	.short	1735
	.short	65535
	.short	1947
	.short	1939
	.short	1799
	.short	1991
	.short	65535
	.short	158
	.short	94
	.short	13
	.short	0
	.short	131
	.short	414
	.short	286
	.short	397
	.short	322
	.short	259
	.short	670
	.short	606
	.short	653
	.short	706
	.short	643
	.short	990
	.short	798
	.short	973
	.short	898
	.short	899
	.short	1246
	.short	1182
	.short	1101
	.short	1090
	.short	1218
	.short	1438
	.short	1374
	.short	1421
	.short	1410
	.short	1346
	.short	1758
	.short	1566
	.short	1549
	.short	1666
	.short	1730
	.short	1822
	.short	1950
	.short	1805
	.short	1922
	.short	1986
	.short	222
	.short	30
	.short	141
	.short	130
	.short	3
	.short	478
	.short	350
	.short	333
	.short	450
	.short	451
	.short	542
	.short	734
	.short	525
	.short	705
	.short	577
	.short	926
	.short	862
	.short	845
	.short	962
	.short	963
	.short	1118
	.short	1054
	.short	1229
	.short	1154
	.short	1219
	.short	1502
	.short	1310
	.short	1293
	.short	1472
	.short	1411
	.short	1630
	.short	1694
	.short	1677
	.short	1603
	.short	1537
	.short	1886
	.short	2014
	.short	1997
	.short	1794
	.short	1795
	.short	90
	.short	217
	.short	81
	.short	65535
	.short	65535
	.short	410
	.short	409
	.short	401
	.short	65535
	.short	65535
	.short	730
	.short	537
	.short	721
	.short	65535
	.short	65535
	.short	922
	.short	793
	.short	977
	.short	65535
	.short	65535
	.short	1114
	.short	1113
	.short	1041
	.short	65535
	.short	65535
	.short	1306
	.short	1369
	.short	1425
	.short	65535
	.short	65535
	.short	1626
	.short	1561
	.short	1745
	.short	65535
	.short	65535
	.short	2010
	.short	2009
	.short	1937
	.short	65535
	.short	65535
	.short	153
	.short	25
	.short	210
	.short	65535
	.short	65535
	.short	345
	.short	281
	.short	466
	.short	65535
	.short	65535
	.short	601
	.short	665
	.short	658
	.short	65535
	.short	65535
	.short	921
	.short	857
	.short	850
	.short	65535
	.short	65535
	.short	1049
	.short	1241
	.short	1234
	.short	65535
	.short	65535
	.short	1497
	.short	1305
	.short	1426
	.short	65535
	.short	65535
	.short	1625
	.short	1753
	.short	1682
	.short	65535
	.short	65535
	.short	1881
	.short	1945
	.short	1810
	.short	65535
	.short	65535
	.short	216
	.short	11
	.short	202
	.short	8
	.short	65535
	.short	408
	.short	459
	.short	458
	.short	264
	.short	65535
	.short	728
	.short	523
	.short	650
	.short	648
	.short	65535
	.short	856
	.short	779
	.short	778
	.short	904
	.short	65535
	.short	1240
	.short	1035
	.short	1162
	.short	1224
	.short	65535
	.short	1496
	.short	1355
	.short	1290
	.short	1416
	.short	65535
	.short	1752
	.short	1547
	.short	1674
	.short	1672
	.short	65535
	.short	2008
	.short	1931
	.short	1866
	.short	1992
	.short	65535
	.short	27
	.short	215
	.short	5
	.short	69
	.short	65535
	.short	283
	.short	407
	.short	389
	.short	261
	.short	65535
	.short	731
	.short	727
	.short	645
	.short	517
	.short	65535
	.short	923
	.short	791
	.short	965
	.short	901
	.short	65535
	.short	1243
	.short	1047
	.short	1221
	.short	1029
	.short	65535
	.short	1307
	.short	1495
	.short	1413
	.short	1285
	.short	65535
	.short	1691
	.short	1687
	.short	1733
	.short	1669
	.short	65535
	.short	1883
	.short	1879
	.short	1989
	.short	1861
	.short	65535
	.size	_ZL7idx_tab, 2560

	.type	__hip_cuid_794236f6d9ab0dff,@object
